# next-unit operand requests issued after the partial-result exchange writes (exchange data reaches the barrier first)
# baseline (speedup 1.0000x reference)
.Lkq_skip_b:
	s_waitcnt lgkmcnt(0)
	s_barrier
	s_and_saveexec_b64 s[0:1], s[40:41]
	s_cbranch_execz .LBB0_517
	s_waitcnt vmcnt(16)
	v_lshl_add_u32 v67, v172, 2, v194
	ds_read2st64_b32 v[68:69], v67 offset1:1
	ds_read2st64_b32 v[96:97], v67 offset0:2 offset1:3
	ds_read2st64_b32 v[98:99], v67 offset0:4 offset1:5
	ds_read2st64_b32 v[100:101], v67 offset0:6 offset1:7
	ds_read2st64_b32 v[102:103], v67 offset0:8 offset1:9
	ds_read2st64_b32 v[104:105], v67 offset0:10 offset1:11
	ds_read2st64_b32 v[106:107], v67 offset0:12 offset1:13
	ds_read2st64_b32 v[108:109], v67 offset0:14 offset1:15
	ds_read2st64_b32 v[110:111], v67 offset0:16 offset1:17
	ds_read2st64_b32 v[112:113], v67 offset0:18 offset1:19
	ds_read2st64_b32 v[114:115], v67 offset0:20 offset1:21
	ds_read2st64_b32 v[116:117], v67 offset0:22 offset1:23
	ds_read2st64_b32 v[118:119], v67 offset0:24 offset1:25
	ds_read2st64_b32 v[120:121], v67 offset0:26 offset1:27
	ds_read2st64_b32 v[122:123], v67 offset0:28 offset1:29
	ds_read2st64_b32 v[124:125], v67 offset0:30 offset1:31
	ds_read2st64_b32 v[126:127], v67 offset0:32 offset1:33
	ds_read2st64_b32 v[128:129], v67 offset0:34 offset1:35
	ds_read2st64_b32 v[130:131], v67 offset0:36 offset1:37
	ds_read2st64_b32 v[132:133], v67 offset0:38 offset1:39
	ds_read2st64_b32 v[134:135], v67 offset0:40 offset1:41
	ds_read2st64_b32 v[136:137], v67 offset0:42 offset1:43
	ds_read2st64_b32 v[138:139], v67 offset0:44 offset1:45
	ds_read2st64_b32 v[140:141], v67 offset0:46 offset1:47
	ds_read2st64_b32 v[142:143], v67 offset0:48 offset1:49
	ds_read2st64_b32 v[144:145], v67 offset0:50 offset1:51
	ds_read2st64_b32 v[146:147], v67 offset0:52 offset1:53
	ds_read2st64_b32 v[148:149], v67 offset0:54 offset1:55
	ds_read2st64_b32 v[150:151], v67 offset0:56 offset1:57
	ds_read2st64_b32 v[152:153], v67 offset0:58 offset1:59
	ds_read2st64_b32 v[154:155], v67 offset0:60 offset1:61
	ds_read2st64_b32 v[156:157], v67 offset0:62 offset1:63
	ds_read2st64_b32 v[158:159], v67 offset0:64 offset1:65
	v_max_f32_e32 v70, v204, v204
	v_readlane_b32 s36, v250, 50
	v_readlane_b32 s37, v250, 51
	v_and_b32_e32 v75, 15, v172
	v_lshrrev_b32_e32 v76, 4, v172
	v_mul_u32_u24_e32 v75, 0x210, v75
	v_lshl_add_u32 v75, v76, 3, v75
	v_add_u32_e32 v75, v75, v193
	v_lshrrev_b32_e32 v76, 5, v172
	v_mul_u32_u24_e32 v76, 0x210, v76
	v_and_b32_e32 v77, 31, v172
	v_lshl_add_u32 v76, v77, 4, v76
	v_add_u32_e32 v76, v76, v193
	s_waitcnt lgkmcnt(0)
	v_max_f32_e32 v66, v68, v68
	v_max_f32_e32 v66, v70, v66
	v_sub_f32_e32 v70, v204, v66
	v_sub_f32_e32 v66, v68, v66
	v_exp_f32_e32 v70, v70
	v_exp_f32_e32 v71, v66
	v_mov_b32_e32 v165, v69
	v_lshl_add_u64 v[64:65], v[174:175], 1, s[36:37]
	v_lshlrev_b32_e32 v72, 4, v172
	v_mov_b32_e32 v73, 0
	v_pk_mul_f32 v[68:69], v[164:165], v[70:71]
	v_lshl_add_u64 v[64:65], v[64:65], 0, v[72:73]
	v_add_f32_e32 v66, v68, v69
	v_div_scale_f32 v68, s[36:37], v66, v66, 1.0
	v_rcp_f32_e32 v69, v68
	s_nop 0
	v_fma_f32 v72, -v68, v69, 1.0
	v_fmac_f32_e32 v69, v72, v69
	v_div_scale_f32 v72, vcc, 1.0, v66, 1.0
	v_mul_f32_e32 v73, v72, v69
	v_fma_f32 v74, -v68, v73, v72
	v_fmac_f32_e32 v73, v74, v69
	v_fma_f32 v68, -v68, v73, v72
	v_div_fmas_f32 v68, v68, v69, v73
	v_div_fixup_f32 v68, v68, v66, 1.0
	v_mul_f32_e32 v66, v70, v68
	v_mul_f32_e32 v68, v71, v68
	s_mov_b64 s[36:37], 0x1000
	v_lshl_add_u64 v[78:79], v[64:65], 0, s[36:37]
	v_pk_mul_f32 v[96:97], v[68:69], v[96:97] op_sel_hi:[0,1]
	v_pk_mul_f32 v[98:99], v[68:69], v[98:99] op_sel_hi:[0,1]
	v_pk_fma_f32 v[60:61], v[66:67], v[60:61], v[96:97] op_sel_hi:[0,1,1]
	v_pk_fma_f32 v[62:63], v[66:67], v[62:63], v[98:99] op_sel_hi:[0,1,1]
	v_cvt_pk_bf16_f32 v60, v60, v61
	v_cvt_pk_bf16_f32 v61, v62, v63
	ds_write_b64 v75, v[60:61]
	v_pk_mul_f32 v[100:101], v[68:69], v[100:101] op_sel_hi:[0,1]
	v_pk_mul_f32 v[102:103], v[68:69], v[102:103] op_sel_hi:[0,1]
	v_pk_fma_f32 v[56:57], v[66:67], v[56:57], v[100:101] op_sel_hi:[0,1,1]
	v_pk_fma_f32 v[58:59], v[66:67], v[58:59], v[102:103] op_sel_hi:[0,1,1]
	v_cvt_pk_bf16_f32 v56, v56, v57
	v_cvt_pk_bf16_f32 v57, v58, v59
	ds_write_b64 v75, v[56:57] offset:32
	v_pk_mul_f32 v[104:105], v[68:69], v[104:105] op_sel_hi:[0,1]
	v_pk_mul_f32 v[106:107], v[68:69], v[106:107] op_sel_hi:[0,1]
	v_pk_fma_f32 v[52:53], v[66:67], v[52:53], v[104:105] op_sel_hi:[0,1,1]
	v_pk_fma_f32 v[54:55], v[66:67], v[54:55], v[106:107] op_sel_hi:[0,1,1]
	v_cvt_pk_bf16_f32 v52, v52, v53
	v_cvt_pk_bf16_f32 v53, v54, v55
	ds_write_b64 v75, v[52:53] offset:64
	v_pk_mul_f32 v[108:109], v[68:69], v[108:109] op_sel_hi:[0,1]
	v_pk_mul_f32 v[110:111], v[68:69], v[110:111] op_sel_hi:[0,1]
	v_pk_fma_f32 v[48:49], v[66:67], v[48:49], v[108:109] op_sel_hi:[0,1,1]
	v_pk_fma_f32 v[50:51], v[66:67], v[50:51], v[110:111] op_sel_hi:[0,1,1]
	v_cvt_pk_bf16_f32 v48, v48, v49
	v_cvt_pk_bf16_f32 v49, v50, v51
	ds_write_b64 v75, v[48:49] offset:96
	v_pk_mul_f32 v[112:113], v[68:69], v[112:113] op_sel_hi:[0,1]
	v_pk_mul_f32 v[114:115], v[68:69], v[114:115] op_sel_hi:[0,1]
	v_pk_fma_f32 v[44:45], v[66:67], v[44:45], v[112:113] op_sel_hi:[0,1,1]
	v_pk_fma_f32 v[46:47], v[66:67], v[46:47], v[114:115] op_sel_hi:[0,1,1]
	v_cvt_pk_bf16_f32 v44, v44, v45
	v_cvt_pk_bf16_f32 v45, v46, v47
	ds_write_b64 v75, v[44:45] offset:128
	v_pk_mul_f32 v[116:117], v[68:69], v[116:117] op_sel_hi:[0,1]
	v_pk_mul_f32 v[118:119], v[68:69], v[118:119] op_sel_hi:[0,1]
	v_pk_fma_f32 v[40:41], v[66:67], v[40:41], v[116:117] op_sel_hi:[0,1,1]
	v_pk_fma_f32 v[42:43], v[66:67], v[42:43], v[118:119] op_sel_hi:[0,1,1]
	v_cvt_pk_bf16_f32 v40, v40, v41
	v_cvt_pk_bf16_f32 v41, v42, v43
	ds_write_b64 v75, v[40:41] offset:160
	v_pk_mul_f32 v[120:121], v[68:69], v[120:121] op_sel_hi:[0,1]
	v_pk_mul_f32 v[122:123], v[68:69], v[122:123] op_sel_hi:[0,1]
	v_pk_fma_f32 v[36:37], v[66:67], v[36:37], v[120:121] op_sel_hi:[0,1,1]
	v_pk_fma_f32 v[38:39], v[66:67], v[38:39], v[122:123] op_sel_hi:[0,1,1]
	v_cvt_pk_bf16_f32 v36, v36, v37
	v_cvt_pk_bf16_f32 v37, v38, v39
	ds_write_b64 v75, v[36:37] offset:192
	v_pk_mul_f32 v[124:125], v[68:69], v[124:125] op_sel_hi:[0,1]
	v_pk_mul_f32 v[126:127], v[68:69], v[126:127] op_sel_hi:[0,1]
	v_pk_fma_f32 v[32:33], v[66:67], v[32:33], v[124:125] op_sel_hi:[0,1,1]
	v_pk_fma_f32 v[34:35], v[66:67], v[34:35], v[126:127] op_sel_hi:[0,1,1]
	v_cvt_pk_bf16_f32 v32, v32, v33
	v_cvt_pk_bf16_f32 v33, v34, v35
	ds_write_b64 v75, v[32:33] offset:224
	v_pk_mul_f32 v[128:129], v[68:69], v[128:129] op_sel_hi:[0,1]
	v_pk_mul_f32 v[130:131], v[68:69], v[130:131] op_sel_hi:[0,1]
	v_pk_fma_f32 v[28:29], v[66:67], v[28:29], v[128:129] op_sel_hi:[0,1,1]
	v_pk_fma_f32 v[30:31], v[66:67], v[30:31], v[130:131] op_sel_hi:[0,1,1]
	v_cvt_pk_bf16_f32 v28, v28, v29
	v_cvt_pk_bf16_f32 v29, v30, v31
	ds_write_b64 v75, v[28:29] offset:256
	v_pk_mul_f32 v[132:133], v[68:69], v[132:133] op_sel_hi:[0,1]
	v_pk_mul_f32 v[134:135], v[68:69], v[134:135] op_sel_hi:[0,1]
	v_pk_fma_f32 v[24:25], v[66:67], v[24:25], v[132:133] op_sel_hi:[0,1,1]
	v_pk_fma_f32 v[26:27], v[66:67], v[26:27], v[134:135] op_sel_hi:[0,1,1]
	v_cvt_pk_bf16_f32 v24, v24, v25
	v_cvt_pk_bf16_f32 v25, v26, v27
	ds_write_b64 v75, v[24:25] offset:288
	v_pk_mul_f32 v[136:137], v[68:69], v[136:137] op_sel_hi:[0,1]
	v_pk_mul_f32 v[138:139], v[68:69], v[138:139] op_sel_hi:[0,1]
	v_pk_fma_f32 v[20:21], v[66:67], v[20:21], v[136:137] op_sel_hi:[0,1,1]
	v_pk_fma_f32 v[22:23], v[66:67], v[22:23], v[138:139] op_sel_hi:[0,1,1]
	v_cvt_pk_bf16_f32 v20, v20, v21
	v_cvt_pk_bf16_f32 v21, v22, v23
	ds_write_b64 v75, v[20:21] offset:320
	v_pk_mul_f32 v[140:141], v[68:69], v[140:141] op_sel_hi:[0,1]
	v_pk_mul_f32 v[142:143], v[68:69], v[142:143] op_sel_hi:[0,1]
	v_pk_fma_f32 v[16:17], v[66:67], v[16:17], v[140:141] op_sel_hi:[0,1,1]
	v_pk_fma_f32 v[18:19], v[66:67], v[18:19], v[142:143] op_sel_hi:[0,1,1]
	v_cvt_pk_bf16_f32 v16, v16, v17
	v_cvt_pk_bf16_f32 v17, v18, v19
	ds_write_b64 v75, v[16:17] offset:352
	v_pk_mul_f32 v[144:145], v[68:69], v[144:145] op_sel_hi:[0,1]
	v_pk_mul_f32 v[146:147], v[68:69], v[146:147] op_sel_hi:[0,1]
	v_pk_fma_f32 v[12:13], v[66:67], v[12:13], v[144:145] op_sel_hi:[0,1,1]
	v_pk_fma_f32 v[14:15], v[66:67], v[14:15], v[146:147] op_sel_hi:[0,1,1]
	v_cvt_pk_bf16_f32 v12, v12, v13
	v_cvt_pk_bf16_f32 v13, v14, v15
	ds_write_b64 v75, v[12:13] offset:384
	v_pk_mul_f32 v[148:149], v[68:69], v[148:149] op_sel_hi:[0,1]
	v_pk_mul_f32 v[150:151], v[68:69], v[150:151] op_sel_hi:[0,1]
	v_pk_fma_f32 v[8:9], v[66:67], v[8:9], v[148:149] op_sel_hi:[0,1,1]
	v_pk_fma_f32 v[10:11], v[66:67], v[10:11], v[150:151] op_sel_hi:[0,1,1]
	v_cvt_pk_bf16_f32 v8, v8, v9
	v_cvt_pk_bf16_f32 v9, v10, v11
	ds_write_b64 v75, v[8:9] offset:416
	v_pk_mul_f32 v[152:153], v[68:69], v[152:153] op_sel_hi:[0,1]
	v_pk_mul_f32 v[154:155], v[68:69], v[154:155] op_sel_hi:[0,1]
	v_pk_fma_f32 v[4:5], v[66:67], v[4:5], v[152:153] op_sel_hi:[0,1,1]
	v_pk_fma_f32 v[6:7], v[66:67], v[6:7], v[154:155] op_sel_hi:[0,1,1]
	v_cvt_pk_bf16_f32 v4, v4, v5
	v_cvt_pk_bf16_f32 v5, v6, v7
	ds_write_b64 v75, v[4:5] offset:448
	v_pk_mul_f32 v[156:157], v[68:69], v[156:157] op_sel_hi:[0,1]
	v_pk_mul_f32 v[158:159], v[68:69], v[158:159] op_sel_hi:[0,1]
	v_pk_fma_f32 v[0:1], v[66:67], v[0:1], v[156:157] op_sel_hi:[0,1,1]
	v_pk_fma_f32 v[2:3], v[66:67], v[2:3], v[158:159] op_sel_hi:[0,1,1]
	v_cvt_pk_bf16_f32 v0, v0, v1
	v_cvt_pk_bf16_f32 v1, v2, v3
	ds_write_b64 v75, v[0:1] offset:480
	s_waitcnt lgkmcnt(0)
	ds_read_b128 v[96:99], v76
	ds_read_b128 v[100:103], v76 offset:1056
	ds_read_b128 v[104:107], v76 offset:2112
	ds_read_b128 v[108:111], v76 offset:3168
	ds_read_b128 v[112:115], v76 offset:4224
	ds_read_b128 v[116:119], v76 offset:5280
	ds_read_b128 v[120:123], v76 offset:6336
	ds_read_b128 v[124:127], v76 offset:7392
	s_waitcnt lgkmcnt(7)
	global_store_dwordx4 v[64:65], v[96:99], off
	s_waitcnt lgkmcnt(6)
	global_store_dwordx4 v[64:65], v[100:103], off offset:1024
	s_waitcnt lgkmcnt(5)
	global_store_dwordx4 v[64:65], v[104:107], off offset:2048
	s_waitcnt lgkmcnt(4)
	global_store_dwordx4 v[64:65], v[108:111], off offset:3072
	s_waitcnt lgkmcnt(3)
	global_store_dwordx4 v[78:79], v[112:115], off
	s_waitcnt lgkmcnt(2)
	global_store_dwordx4 v[78:79], v[116:119], off offset:1024
	s_waitcnt lgkmcnt(1)
	global_store_dwordx4 v[78:79], v[120:123], off offset:2048
	s_waitcnt lgkmcnt(0)
	global_store_dwordx4 v[78:79], v[124:127], off offset:3072
